# speedup vs baseline: 1.0063x; 1.0039x over previous
; __device__ __forceinline__ unsigned xb_ld(unsigned* p)              { return __hip_atomic_load(p, __ATOMIC_RELAXED, __HIP_MEMORY_SCOPE_AGENT); }
; __device__ __forceinline__ void xcd_barrier_complete(unsigned* bar, unsigned x, unsigned& nloc, unsigned& nx) {
;     ...
;     for (;;) {
;         sum = 0u; cnt = 0u; mine = 0u;
; #pragma unroll
;         for (unsigned j = 0; j < 16; ++j) { const unsigned c = xb_ld(&bar[XB_XCNT(j)]); sum += c; cnt += (c > 0u) ? 1u : 0u; mine = (j == x) ? c : mine; }
;         if (sum == G) break;
;         __builtin_amdgcn_s_sleep(1);
;         if ((++sp & 255u) == 0u) { if (xb_ld(&bar[XB_TMO])) break; if (sp > XB_SPIN_CAP) { atomicAdd(&bar[XB_TMO], 1u); break; } }
;     }
;     nloc = mine > 0u ? mine : 1u; nx = cnt > 0u ? cnt : 1u;
.LBB0_230:
	v_mov_b64_e32 v[12:13], s[42:43]
	flat_load_dword v1, v[12:13] offset:1024 sc1
	flat_load_dword v0, v[12:13] offset:1280 sc1
	flat_load_dword v3, v[12:13] offset:1536 sc1
	flat_load_dword v4, v[12:13] offset:1792 sc1
	flat_load_dword v5, v[12:13] offset:2048 sc1
	flat_load_dword v6, v[12:13] offset:2304 sc1
	flat_load_dword v7, v[12:13] offset:2560 sc1
	flat_load_dword v8, v[12:13] offset:2816 sc1
	flat_load_dword v9, v[12:13] offset:3072 sc1
	flat_load_dword v10, v[12:13] offset:3328 sc1
	flat_load_dword v11, v[12:13] offset:3584 sc1
	v_mov_b64_e32 v[14:15], s[0:1]
	flat_load_dword v20, v[14:15] sc1
	v_mov_b64_e32 v[16:17], s[2:3]
	flat_load_dword v21, v[16:17] sc1
	v_mov_b64_e32 v[18:19], s[4:5]
	flat_load_dword v22, v[18:19] sc1
	v_mov_b64_e32 v[24:25], s[6:7]
	flat_load_dword v23, v[24:25] sc1
	flat_load_dword v12, v[12:13] offset:3840 sc1
	s_or_b64 s[18:19], s[18:19], exec
	s_or_b64 s[16:17], s[16:17], exec
	s_waitcnt vmcnt(0) lgkmcnt(0)
	v_mov_b32_e32 v13, v20
	v_mov_b32_e32 v14, v21
	v_mov_b32_e32 v15, v22
	v_mov_b32_e32 v16, v23
	v_add_u32_e32 v17, v0, v1
	v_add_u32_e32 v17, v17, v3
	v_add_u32_e32 v17, v17, v4
	v_add_u32_e32 v17, v17, v5
	v_add_u32_e32 v17, v17, v6
	v_add_u32_e32 v17, v17, v7
	v_add_u32_e32 v17, v17, v8
	v_add_u32_e32 v17, v17, v9
	v_add_u32_e32 v17, v17, v10
	v_add_u32_e32 v17, v17, v11
	v_add_u32_e32 v17, v17, v12
	v_add_u32_e32 v17, v17, v13
	v_add_u32_e32 v17, v17, v14
	v_add_u32_e32 v17, v17, v15
	v_add_u32_e32 v17, v17, v16
	v_cmp_ne_u32_e32 vcc, s76, v17
	s_and_saveexec_b64 s[20:21], vcc
	s_cbranch_execz .LBB0_229
	s_and_b32 s24, s30, 0xff
	s_mov_b64 s[22:23], -1
	s_cmp_eq_u32 s24, 0
	s_mov_b64 s[26:27], -1
	s_mov_b64 s[24:25], -1
	s_sleep 1
	s_cbranch_scc1 .LBB0_233
	s_and_saveexec_b64 s[28:29], s[26:27]
	s_cbranch_execz .LBB0_228
	s_branch .LBB0_236
